# final norm phase: 7 g chunks prefetched once per iteration into free quads, per-j vmcnt(0) waits removed so f32 output stores stream; 2-wait-state pads after 128-bit stores
# baseline (speedup 1.0000x reference)
; __device__ __forceinline__ float bf_lo(unsigned u) { return __uint_as_float(u << 16); }
; __device__ __forceinline__ float bf_hi(unsigned u) { return __uint_as_float(u & 0xffff0000u); }
; __device__ __forceinline__ void phase_final(const _Float16* xin_h, const bf16_t* dl, const float* g, float* out) {
;     ...
;     for (int row0 = blockIdx.x * NWAVES + wave; row0 < MTOK; row0 += 2 * NW) {
;         f32x4 v[2][8]; u32x2 d[2][8];
; #pragma unroll
;         for (int q = 0; q < 2; ++q) { const int row = min(row0 + q * NW, MTOK - 1); const f16x4* xr = (const f16x4*)(xin_h + (size_t)row * XH_PITCH) + lane; const u32x2* dr = (const u32x2*)(dl + (size_t)row * DM) + lane;
; #pragma unroll
;             for (int j = 0; j < 8; ++j) { const f16x4 t = xr[64 * j]; v[q][j] = (f32x4){(float)t.x, (float)t.y, (float)t.z, (float)t.w}; d[q][j] = dr[64 * j]; } }
;         asm volatile("s_waitcnt vmcnt(0)" ::: "memory");
; #pragma unroll
;         for (int q = 0; q < 2; ++q) { const int row = row0 + q * NW; float s = 0.f;
;             if (row >= MTOK) break;
; #pragma unroll
;             for (int j = 0; j < 8; ++j) { v[q][j].x += bf_lo(d[q][j].x); v[q][j].y += bf_hi(d[q][j].x); v[q][j].z += bf_lo(d[q][j].y); v[q][j].w += bf_hi(d[q][j].y);
;                 s += (v[q][j].x * v[q][j].x + v[q][j].y * v[q][j].y) + (v[q][j].z * v[q][j].z + v[q][j].w * v[q][j].w); }
.LBB0_755:
	s_ashr_i32 s13, s12, 31
	s_lshl_b64 s[16:17], s[12:13], 13
	v_lshl_add_u64 v[18:19], v[2:3], 0, s[16:17]
	global_load_dwordx2 v[42:43], v[18:19], off
	s_lshl_b64 s[2:3], s[12:13], 12
	v_lshl_add_u64 v[20:21], v[4:5], 0, s[2:3]
	global_load_dwordx2 v[44:45], v[20:21], off
	global_load_dwordx2 v[46:47], v[18:19], off offset:512
	global_load_dwordx2 v[48:49], v[20:21], off offset:512
	global_load_dwordx2 v[50:51], v[18:19], off offset:1024
	global_load_dwordx2 v[52:53], v[20:21], off offset:1024
	global_load_dwordx2 v[54:55], v[18:19], off offset:1536
	global_load_dwordx2 v[56:57], v[20:21], off offset:1536
	global_load_dwordx2 v[64:65], v[18:19], off offset:2048
	global_load_dwordx2 v[70:71], v[18:19], off offset:2560
	global_load_dwordx2 v[74:75], v[18:19], off offset:3072
	global_load_dwordx2 v[40:41], v[18:19], off offset:3584
	global_load_dwordx2 v[72:73], v[20:21], off offset:2048
	global_load_dwordx2 v[76:77], v[20:21], off offset:2560
	global_load_dwordx2 v[78:79], v[20:21], off offset:3072
	global_load_dwordx2 v[38:39], v[20:21], off offset:3584
	s_add_i32 s12, s12, s21
	s_min_i32 s2, s12, 0x3fff
	s_ashr_i32 s3, s2, 31
	s_lshl_b64 s[4:5], s[2:3], 13
	s_lshl_b64 s[2:3], s[2:3], 12
	v_lshl_add_u64 v[34:35], v[2:3], 0, s[4:5]
	v_lshl_add_u64 v[36:37], v[4:5], 0, s[2:3]
	global_load_dwordx2 v[30:31], v[34:35], off
	global_load_dwordx2 v[26:27], v[34:35], off offset:512
	global_load_dwordx2 v[22:23], v[34:35], off offset:1024
	global_load_dwordx2 v[20:21], v[34:35], off offset:1536
	global_load_dwordx2 v[32:33], v[36:37], off
	global_load_dwordx2 v[28:29], v[36:37], off offset:512
	global_load_dwordx2 v[24:25], v[36:37], off offset:1024
	global_load_dwordx2 v[18:19], v[36:37], off offset:1536
	s_cmpk_gt_i32 s12, 0x3fff
	s_waitcnt vmcnt(0) lgkmcnt(0)
	v_lshlrev_b32_e32 v60, 16, v44
	v_cvt_f32_f16_e32 v62, v46
	v_cvt_f32_f16_sdwa v63, v46 dst_sel:DWORD dst_unused:UNUSED_PAD src0_sel:WORD_1
	v_cvt_f32_f16_e32 v58, v42
	v_cvt_f32_f16_sdwa v59, v42 dst_sel:DWORD dst_unused:UNUSED_PAD src0_sel:WORD_1
	v_cvt_f32_f16_e32 v42, v43
	v_cvt_f32_f16_sdwa v43, v43 dst_sel:DWORD dst_unused:UNUSED_PAD src0_sel:WORD_1
	v_cvt_f32_f16_e32 v46, v47
	v_cvt_f32_f16_sdwa v47, v47 dst_sel:DWORD dst_unused:UNUSED_PAD src0_sel:WORD_1
	v_cvt_f32_f16_e32 v82, v50
	v_cvt_f32_f16_sdwa v83, v50 dst_sel:DWORD dst_unused:UNUSED_PAD src0_sel:WORD_1
	v_cvt_f32_f16_e32 v86, v51
	v_cvt_f32_f16_sdwa v87, v51 dst_sel:DWORD dst_unused:UNUSED_PAD src0_sel:WORD_1
	v_and_b32_e32 v61, 0xffff0000, v44
	v_lshlrev_b32_e32 v44, 16, v45
	v_and_b32_e32 v45, 0xffff0000, v45
	v_lshlrev_b32_e32 v80, 16, v48
	v_and_b32_e32 v81, 0xffff0000, v48
	v_lshlrev_b32_e32 v48, 16, v49
	v_and_b32_e32 v49, 0xffff0000, v49
	v_lshlrev_b32_e32 v84, 16, v52
	v_and_b32_e32 v85, 0xffff0000, v52
	v_lshlrev_b32_e32 v52, 16, v53
	v_and_b32_e32 v53, 0xffff0000, v53
	v_pk_add_f32 v[66:67], v[58:59], v[60:61]
	v_pk_add_f32 v[68:69], v[42:43], v[44:45]
	v_pk_add_f32 v[58:59], v[62:63], v[80:81]
	v_pk_add_f32 v[60:61], v[46:47], v[48:49]
	v_pk_add_f32 v[50:51], v[82:83], v[84:85]
	v_pk_add_f32 v[52:53], v[86:87], v[52:53]
	v_mov_b32_e32 v44, v67
	v_mov_b32_e32 v45, v59
	v_mov_b32_e32 v48, v69
	v_mov_b32_e32 v49, v61
	v_mov_b32_e32 v62, v51
	v_mov_b32_e32 v63, v53
	v_cvt_f32_f16_e32 v88, v54
	v_cvt_f32_f16_sdwa v89, v54 dst_sel:DWORD dst_unused:UNUSED_PAD src0_sel:WORD_1
	v_cvt_f32_f16_e32 v92, v55
	v_cvt_f32_f16_sdwa v93, v55 dst_sel:DWORD dst_unused:UNUSED_PAD src0_sel:WORD_1
	v_mov_b32_e32 v42, v66
	v_mov_b32_e32 v43, v58
	v_mov_b32_e32 v46, v68
	v_mov_b32_e32 v47, v60
	v_mov_b32_e32 v54, v50
	v_mov_b32_e32 v55, v52
	v_pk_mul_f32 v[44:45], v[44:45], v[44:45]
	v_pk_mul_f32 v[48:49], v[48:49], v[48:49]
	v_pk_mul_f32 v[62:63], v[62:63], v[62:63]
	v_pk_fma_f32 v[42:43], v[42:43], v[42:43], v[44:45]
	v_pk_fma_f32 v[44:45], v[46:47], v[46:47], v[48:49]
	v_pk_fma_f32 v[46:47], v[54:55], v[54:55], v[62:63]
	v_lshlrev_b32_e32 v90, 16, v56
	v_and_b32_e32 v91, 0xffff0000, v56
	v_pk_add_f32 v[42:43], v[42:43], v[44:45]
	v_pk_add_f32 v[44:45], v[46:47], v[46:47] op_sel:[0,1] op_sel_hi:[1,0]
	v_lshlrev_b32_e32 v46, 16, v57
	v_and_b32_e32 v47, 0xffff0000, v57
	v_cvt_f32_f16_e32 v56, v64
	v_cvt_f32_f16_sdwa v57, v64 dst_sel:DWORD dst_unused:UNUSED_PAD src0_sel:WORD_1
	v_cvt_f32_f16_e32 v64, v65
	v_cvt_f32_f16_sdwa v65, v65 dst_sel:DWORD dst_unused:UNUSED_PAD src0_sel:WORD_1
	v_pk_add_f32 v[54:55], v[88:89], v[90:91]
	v_pk_add_f32 v[62:63], v[92:93], v[46:47]
	v_mul_f32_e32 v0, v55, v55
	v_lshlrev_b32_e32 v80, 16, v72
	v_and_b32_e32 v81, 0xffff0000, v72
	v_lshlrev_b32_e32 v72, 16, v73
	v_and_b32_e32 v73, 0xffff0000, v73
	v_pk_fma_f32 v[46:47], v[54:55], v[54:55], v[0:1] op_sel_hi:[1,1,0]
	v_mul_f32_e32 v0, v63, v63
	v_pk_add_f32 v[56:57], v[56:57], v[80:81]
	v_pk_add_f32 v[64:65], v[64:65], v[72:73]
	v_pk_add_f32 v[42:43], v[42:43], v[42:43] op_sel:[0,1] op_sel_hi:[1,0]
	v_pk_fma_f32 v[48:49], v[62:63], v[62:63], v[0:1] op_sel_hi:[1,1,0]
	v_pk_mul_f32 v[72:73], v[56:57], v[56:57]
	v_pk_mul_f32 v[80:81], v[64:65], v[64:65]
	v_mov_b32_e32 v43, v72
	v_mov_b32_e32 v45, v73
	v_mov_b32_e32 v47, v80
	v_mov_b32_e32 v49, v81
	v_pk_add_f32 v[42:43], v[42:43], v[44:45]
	v_pk_add_f32 v[44:45], v[46:47], v[48:49]
	v_cvt_f32_f16_e32 v48, v71
	v_pk_add_f32 v[42:43], v[42:43], v[44:45]
	v_cvt_f32_f16_e32 v44, v70
	v_cvt_f32_f16_sdwa v45, v70 dst_sel:DWORD dst_unused:UNUSED_PAD src0_sel:WORD_1
	v_cvt_f32_f16_sdwa v49, v71 dst_sel:DWORD dst_unused:UNUSED_PAD src0_sel:WORD_1
	v_lshlrev_b32_e32 v46, 16, v76
	v_and_b32_e32 v47, 0xffff0000, v76
	v_pk_add_f32 v[70:71], v[44:45], v[46:47]
	v_lshlrev_b32_e32 v44, 16, v77
; __device__ __forceinline__ float bf_lo(unsigned u) { return __uint_as_float(u << 16); }
; __device__ __forceinline__ float bf_hi(unsigned u) { return __uint_as_float(u & 0xffff0000u); }
; __device__ __forceinline__ void phase_final(const _Float16* xin_h, const bf16_t* dl, const float* g, float* out) {
;     ...
;         for (int q = 0; q < 2; ++q) { const int row = min(row0 + q * NW, MTOK - 1); const f16x4* xr = (const f16x4*)(xin_h + (size_t)row * XH_PITCH) + lane; const u32x2* dr = (const u32x2*)(dl + (size_t)row * DM) + lane;
; #pragma unroll
;             for (int j = 0; j < 8; ++j) { const f16x4 t = xr[64 * j]; v[q][j] = (f32x4){(float)t.x, (float)t.y, (float)t.z, (float)t.w}; d[q][j] = dr[64 * j]; } }
;         asm volatile("s_waitcnt vmcnt(0)" ::: "memory");
; #pragma unroll
;         for (int q = 0; q < 2; ++q) { const int row = row0 + q * NW; float s = 0.f;
;             if (row >= MTOK) break;
; #pragma unroll
;             for (int j = 0; j < 8; ++j) { v[q][j].x += bf_lo(d[q][j].x); v[q][j].y += bf_hi(d[q][j].x); v[q][j].z += bf_lo(d[q][j].y); v[q][j].w += bf_hi(d[q][j].y);
;                 s += (v[q][j].x * v[q][j].x + v[q][j].y * v[q][j].y) + (v[q][j].z * v[q][j].z + v[q][j].w * v[q][j].w); }
;             const float rstd = 1.f / sqrtf(wave_sum(s) * (1.f / DM) + 1e-6f);
;             f32x4* o = (f32x4*)(out + (size_t)row * DM) + lane;
; #pragma unroll
;             for (int j = 0; j < 8; ++j) o[64 * j] = v[q][j] * rstd * *(const f32x4*)(g + 4 * lane + 256 * j); }
	v_and_b32_e32 v45, 0xffff0000, v77
	v_pk_add_f32 v[72:73], v[48:49], v[44:45]
	v_mov_b32_e32 v46, v71
	v_mov_b32_e32 v47, v73
	v_mov_b32_e32 v44, v70
	v_mov_b32_e32 v45, v72
	v_pk_mul_f32 v[46:47], v[46:47], v[46:47]
	v_lshlrev_b32_e32 v48, 16, v78
	v_pk_fma_f32 v[44:45], v[44:45], v[44:45], v[46:47]
	v_cvt_f32_f16_e32 v46, v74
	v_cvt_f32_f16_sdwa v47, v74 dst_sel:DWORD dst_unused:UNUSED_PAD src0_sel:WORD_1
	v_and_b32_e32 v49, 0xffff0000, v78
	v_cvt_f32_f16_e32 v76, v75
	v_cvt_f32_f16_sdwa v77, v75 dst_sel:DWORD dst_unused:UNUSED_PAD src0_sel:WORD_1
	v_pk_add_f32 v[74:75], v[46:47], v[48:49]
	v_lshlrev_b32_e32 v46, 16, v79
	v_and_b32_e32 v47, 0xffff0000, v79
	v_cvt_f32_f16_e32 v78, v40
	v_cvt_f32_f16_sdwa v79, v40 dst_sel:DWORD dst_unused:UNUSED_PAD src0_sel:WORD_1
	v_cvt_f32_f16_e32 v40, v41
	v_cvt_f32_f16_sdwa v41, v41 dst_sel:DWORD dst_unused:UNUSED_PAD src0_sel:WORD_1
	v_pk_add_f32 v[76:77], v[76:77], v[46:47]
	v_mul_f32_e32 v0, v75, v75
	v_lshlrev_b32_e32 v80, 16, v38
	v_and_b32_e32 v81, 0xffff0000, v38
	v_lshlrev_b32_e32 v38, 16, v39
	v_and_b32_e32 v39, 0xffff0000, v39
	v_pk_fma_f32 v[46:47], v[74:75], v[74:75], v[0:1] op_sel_hi:[1,1,0]
	v_mul_f32_e32 v0, v77, v77
	v_pk_add_f32 v[78:79], v[78:79], v[80:81]
	v_pk_add_f32 v[80:81], v[40:41], v[38:39]
	v_pk_add_f32 v[42:43], v[42:43], v[42:43] op_sel:[0,1] op_sel_hi:[1,0]
	v_pk_add_f32 v[44:45], v[44:45], v[44:45] op_sel:[0,1] op_sel_hi:[1,0]
	v_pk_fma_f32 v[48:49], v[76:77], v[76:77], v[0:1] op_sel_hi:[1,1,0]
	v_pk_mul_f32 v[38:39], v[78:79], v[78:79]
	v_pk_mul_f32 v[40:41], v[80:81], v[80:81]
	v_and_b32_e32 v0, 64, v182
	v_mov_b32_e32 v43, v38
	v_mov_b32_e32 v45, v39
	v_mov_b32_e32 v47, v40
	v_mov_b32_e32 v49, v41
	v_add_u32_e32 v86, 64, v0
	v_xor_b32_e32 v0, 1, v182
	v_pk_add_f32 v[38:39], v[42:43], v[44:45]
	v_pk_add_f32 v[40:41], v[46:47], v[48:49]
	v_cmp_lt_i32_e32 vcc, v0, v86
	v_pk_add_f32 v[38:39], v[38:39], v[40:41]
	s_nop 0
	v_cndmask_b32_e32 v0, v182, v0, vcc
	v_add_f32_e32 v40, v38, v39
	v_lshlrev_b32_e32 v0, 2, v0
	ds_bpermute_b32 v41, v0, v40
	global_load_dwordx2 v[46:47], v[34:35], off offset:2048
	global_load_dwordx2 v[42:43], v[34:35], off offset:2560
	global_load_dwordx2 v[38:39], v[34:35], off offset:3072
	s_nop 0
	global_load_dwordx2 v[34:35], v[34:35], off offset:3584
	s_waitcnt lgkmcnt(0)
	v_add_f32_e32 v83, v40, v41
	v_xor_b32_e32 v40, 2, v182
	v_cmp_lt_i32_e32 vcc, v40, v86
	s_nop 1
	v_cndmask_b32_e32 v40, v182, v40, vcc
	v_lshlrev_b32_e32 v82, 2, v40
	global_load_dwordx2 v[48:49], v[36:37], off offset:2048
	global_load_dwordx2 v[44:45], v[36:37], off offset:2560
	global_load_dwordx2 v[40:41], v[36:37], off offset:3072
	s_nop 0
	global_load_dwordx2 v[36:37], v[36:37], off offset:3584
	s_waitcnt vmcnt(0)
	global_load_dwordx4 v[88:91], v[8:9], off
	global_load_dwordx4 v[98:101], v[8:9], off offset:1024
	global_load_dwordx4 v[102:105], v[8:9], off offset:2048
	global_load_dwordx4 v[106:109], v[8:9], off offset:3072
	global_load_dwordx4 v[110:113], v[10:11], off
	global_load_dwordx4 v[114:117], v[12:13], off
	global_load_dwordx4 v[118:121], v[14:15], off
	global_load_dwordx4 v[122:125], v[16:17], off
	ds_bpermute_b32 v84, v82, v83
	s_waitcnt lgkmcnt(0)
	v_add_f32_e32 v84, v83, v84
	v_xor_b32_e32 v83, 4, v182
	v_cmp_lt_i32_e32 vcc, v83, v86
	s_nop 1
	v_cndmask_b32_e32 v83, v182, v83, vcc
	v_lshlrev_b32_e32 v83, 2, v83
	ds_bpermute_b32 v85, v83, v84
	s_waitcnt lgkmcnt(0)
	v_add_f32_e32 v85, v84, v85
	v_xor_b32_e32 v84, 8, v182
	v_cmp_lt_i32_e32 vcc, v84, v86
	s_nop 1
	v_cndmask_b32_e32 v84, v182, v84, vcc
	v_lshlrev_b32_e32 v84, 2, v84
	ds_bpermute_b32 v87, v84, v85
	s_waitcnt lgkmcnt(0)
	v_add_f32_e32 v87, v85, v87
	v_xor_b32_e32 v85, 16, v182
	v_cmp_lt_i32_e32 vcc, v85, v86
	s_nop 1
	v_cndmask_b32_e32 v85, v182, v85, vcc
	v_lshlrev_b32_e32 v85, 2, v85
	ds_bpermute_b32 v92, v85, v87
	s_waitcnt lgkmcnt(0)
	v_add_f32_e32 v87, v87, v92
	v_xor_b32_e32 v92, 32, v182
	v_cmp_lt_i32_e32 vcc, v92, v86
	s_nop 1
	v_cndmask_b32_e32 v86, v182, v92, vcc
	v_lshlrev_b32_e32 v86, 2, v86
	ds_bpermute_b32 v92, v86, v87
	s_waitcnt lgkmcnt(0)
	v_add_f32_e32 v87, v87, v92
	v_fmamk_f32 v87, v87, 0x3a000000, v181
	v_mul_f32_e32 v92, 0x4f800000, v87
	v_cmp_gt_f32_e32 vcc, s7, v87
	s_nop 1
	v_cndmask_b32_e32 v87, v87, v92, vcc
	v_sqrt_f32_e32 v92, v87
	s_nop 0
	v_add_u32_e32 v93, -1, v92
	v_fma_f32 v94, -v93, v92, v87
	v_cmp_ge_f32_e64 s[40:41], 0, v94
	v_add_u32_e32 v94, 1, v92
	s_nop 0
	v_cndmask_b32_e64 v93, v92, v93, s[40:41]
	v_fma_f32 v92, -v94, v92, v87
	v_cmp_lt_f32_e64 s[40:41], 0, v92
	s_nop 1
	v_cndmask_b32_e64 v92, v93, v94, s[40:41]
	v_mul_f32_e32 v93, 0x37800000, v92
	v_cndmask_b32_e32 v92, v92, v93, vcc
	v_cmp_class_f32_e32 vcc, v87, v180
	s_nop 1
	v_cndmask_b32_e32 v87, v92, v87, vcc
	v_div_scale_f32 v92, s[2:3], v87, v87, 1.0
	v_rcp_f32_e32 v93, v92
	s_nop 0
	v_fma_f32 v94, -v92, v93, 1.0
	v_fmac_f32_e32 v93, v94, v93
	v_div_scale_f32 v94, vcc, 1.0, v87, 1.0
	v_mul_f32_e32 v95, v94, v93
	v_fma_f32 v96, -v92, v95, v94
	v_fmac_f32_e32 v95, v96, v93
	v_fma_f32 v92, -v92, v95, v94
	v_div_fmas_f32 v92, v92, v93, v95
	v_div_fixup_f32 v92, v92, v87, 1.0
	v_pk_mul_f32 v[66:67], v[66:67], v[92:93] op_sel_hi:[1,0]
	v_pk_mul_f32 v[68:69], v[68:69], v[92:93] op_sel_hi:[1,0]
	v_lshl_add_u64 v[94:95], v[6:7], 0, s[16:17]
	s_waitcnt vmcnt(0)
; __device__ __forceinline__ float bf_lo(unsigned u) { return __uint_as_float(u << 16); }
; __device__ __forceinline__ float bf_hi(unsigned u) { return __uint_as_float(u & 0xffff0000u); }
; __device__ __forceinline__ void phase_final(const _Float16* xin_h, const bf16_t* dl, const float* g, float* out) {
;     ...
;         for (int q = 0; q < 2; ++q) { const int row = row0 + q * NW; float s = 0.f;
;             if (row >= MTOK) break;
; #pragma unroll
;             for (int j = 0; j < 8; ++j) { v[q][j].x += bf_lo(d[q][j].x); v[q][j].y += bf_hi(d[q][j].x); v[q][j].z += bf_lo(d[q][j].y); v[q][j].w += bf_hi(d[q][j].y);
;                 s += (v[q][j].x * v[q][j].x + v[q][j].y * v[q][j].y) + (v[q][j].z * v[q][j].z + v[q][j].w * v[q][j].w); }
;             const float rstd = 1.f / sqrtf(wave_sum(s) * (1.f / DM) + 1e-6f);
;             f32x4* o = (f32x4*)(out + (size_t)row * DM) + lane;
; #pragma unroll
;             for (int j = 0; j < 8; ++j) o[64 * j] = v[q][j] * rstd * *(const f32x4*)(g + 4 * lane + 256 * j); }
	v_pk_mul_f32 v[68:69], v[90:91], v[68:69]
	v_pk_mul_f32 v[66:67], v[88:89], v[66:67]
	global_store_dwordx4 v[94:95], v[66:69], off
	s_nop 1
	v_mov_b32_e32 v66, v98
	v_mov_b32_e32 v67, v99
	v_mov_b32_e32 v68, v100
	v_mov_b32_e32 v69, v101
	v_pk_mul_f32 v[60:61], v[60:61], v[92:93] op_sel_hi:[1,0]
	v_pk_mul_f32 v[58:59], v[58:59], v[92:93] op_sel_hi:[1,0]
	v_pk_mul_f32 v[52:53], v[52:53], v[92:93] op_sel_hi:[1,0]
	v_pk_mul_f32 v[50:51], v[50:51], v[92:93] op_sel_hi:[1,0]
	v_pk_mul_f32 v[54:55], v[54:55], v[92:93] op_sel_hi:[1,0]
	v_pk_mul_f32 v[56:57], v[56:57], v[92:93] op_sel_hi:[1,0]
	v_pk_mul_f32 v[58:59], v[66:67], v[58:59]
	v_pk_mul_f32 v[60:61], v[68:69], v[60:61]
	global_store_dwordx4 v[94:95], v[58:61], off offset:1024
	s_nop 1
	v_mov_b32_e32 v58, v102
	v_mov_b32_e32 v59, v103
	v_mov_b32_e32 v60, v104
	v_mov_b32_e32 v61, v105
	v_pk_mul_f32 v[50:51], v[58:59], v[50:51]
	v_pk_mul_f32 v[52:53], v[60:61], v[52:53]
	global_store_dwordx4 v[94:95], v[50:53], off offset:2048
	s_nop 1
	v_mov_b32_e32 v50, v106
	v_mov_b32_e32 v51, v107
	v_mov_b32_e32 v52, v108
	v_mov_b32_e32 v53, v109
	v_pk_mul_f32 v[58:59], v[62:63], v[92:93] op_sel_hi:[1,0]
	v_pk_mul_f32 v[50:51], v[50:51], v[54:55]
	v_pk_mul_f32 v[52:53], v[52:53], v[58:59]
	global_store_dwordx4 v[94:95], v[50:53], off offset:3072
	s_nop 1
	v_mov_b32_e32 v50, v110
	v_mov_b32_e32 v51, v111
	v_mov_b32_e32 v52, v112
	v_mov_b32_e32 v53, v113
	v_add_co_u32_e32 v54, vcc, s6, v94
	v_pk_mul_f32 v[58:59], v[64:65], v[92:93] op_sel_hi:[1,0]
	s_nop 0
	v_addc_co_u32_e32 v55, vcc, 0, v95, vcc
	v_pk_mul_f32 v[50:51], v[56:57], v[50:51]
	v_pk_mul_f32 v[52:53], v[58:59], v[52:53]
	global_store_dwordx4 v[54:55], v[50:53], off
	s_nop 1
	v_mov_b32_e32 v50, v114
	v_mov_b32_e32 v51, v115
	v_mov_b32_e32 v52, v116
	v_mov_b32_e32 v53, v117
	v_pk_mul_f32 v[56:57], v[72:73], v[92:93] op_sel_hi:[1,0]
	v_pk_mul_f32 v[58:59], v[70:71], v[92:93] op_sel_hi:[1,0]
	v_pk_mul_f32 v[52:53], v[56:57], v[52:53]
	v_pk_mul_f32 v[50:51], v[58:59], v[50:51]
	global_store_dwordx4 v[54:55], v[50:53], off offset:1024
	s_nop 1
	v_mov_b32_e32 v50, v118
	v_mov_b32_e32 v51, v119
	v_mov_b32_e32 v52, v120
	v_mov_b32_e32 v53, v121
	v_pk_mul_f32 v[56:57], v[76:77], v[92:93] op_sel_hi:[1,0]
	v_pk_mul_f32 v[58:59], v[74:75], v[92:93] op_sel_hi:[1,0]
	v_pk_mul_f32 v[52:53], v[56:57], v[52:53]
	v_pk_mul_f32 v[50:51], v[58:59], v[50:51]
	global_store_dwordx4 v[54:55], v[50:53], off offset:2048
	s_nop 1
	v_mov_b32_e32 v50, v122
	v_mov_b32_e32 v51, v123
	v_mov_b32_e32 v52, v124
	v_mov_b32_e32 v53, v125
	v_pk_mul_f32 v[56:57], v[80:81], v[92:93] op_sel_hi:[1,0]
	v_pk_mul_f32 v[58:59], v[78:79], v[92:93] op_sel_hi:[1,0]
	v_pk_mul_f32 v[52:53], v[56:57], v[52:53]
	v_pk_mul_f32 v[50:51], v[58:59], v[50:51]
	global_store_dwordx4 v[54:55], v[50:53], off offset:3072
	s_cbranch_scc1 .LBB0_754
	s_nop 0
	v_cvt_f32_f16_sdwa v51, v30 dst_sel:DWORD dst_unused:UNUSED_PAD src0_sel:WORD_1
	v_cvt_f32_f16_e32 v50, v30
	v_cvt_f32_f16_sdwa v55, v31 dst_sel:DWORD dst_unused:UNUSED_PAD src0_sel:WORD_1
	v_cvt_f32_f16_e32 v54, v31
	v_lshlrev_b32_e32 v52, 16, v32
	v_and_b32_e32 v53, 0xffff0000, v32
	v_pk_add_f32 v[30:31], v[50:51], v[52:53]
	v_lshlrev_b32_e32 v32, 16, v33
	v_and_b32_e32 v33, 0xffff0000, v33
	v_cvt_f32_f16_sdwa v51, v26 dst_sel:DWORD dst_unused:UNUSED_PAD src0_sel:WORD_1
	v_cvt_f32_f16_e32 v50, v26
	v_pk_add_f32 v[32:33], v[54:55], v[32:33]
	v_cvt_f32_f16_sdwa v55, v27 dst_sel:DWORD dst_unused:UNUSED_PAD src0_sel:WORD_1
	v_cvt_f32_f16_e32 v54, v27
	v_lshlrev_b32_e32 v52, 16, v28
	v_and_b32_e32 v53, 0xffff0000, v28
	v_pk_add_f32 v[26:27], v[50:51], v[52:53]
	v_lshlrev_b32_e32 v28, 16, v29
	v_and_b32_e32 v29, 0xffff0000, v29
	v_pk_add_f32 v[28:29], v[54:55], v[28:29]
	v_mov_b32_e32 v52, v31
	v_mov_b32_e32 v53, v27
	v_mov_b32_e32 v50, v30
	v_mov_b32_e32 v51, v26
	v_pk_mul_f32 v[52:53], v[52:53], v[52:53]
	v_mov_b32_e32 v54, v33
	v_mov_b32_e32 v55, v29
	v_pk_fma_f32 v[50:51], v[50:51], v[50:51], v[52:53]
	v_mov_b32_e32 v52, v32
	v_mov_b32_e32 v53, v28
	v_pk_mul_f32 v[54:55], v[54:55], v[54:55]
	v_cvt_f32_f16_sdwa v57, v23 dst_sel:DWORD dst_unused:UNUSED_PAD src0_sel:WORD_1
	v_pk_fma_f32 v[52:53], v[52:53], v[52:53], v[54:55]
	v_cvt_f32_f16_e32 v56, v23
	v_pk_add_f32 v[50:51], v[50:51], v[52:53]
	v_lshlrev_b32_e32 v54, 16, v24
	v_pk_add_f32 v[52:53], v[50:51], v[50:51] op_sel:[0,1] op_sel_hi:[1,0]
	v_cvt_f32_f16_sdwa v51, v22 dst_sel:DWORD dst_unused:UNUSED_PAD src0_sel:WORD_1
	v_cvt_f32_f16_e32 v50, v22
	v_and_b32_e32 v55, 0xffff0000, v24
	v_lshlrev_b32_e32 v24, 16, v25
	v_and_b32_e32 v25, 0xffff0000, v25
	v_pk_add_f32 v[22:23], v[50:51], v[54:55]
	v_pk_add_f32 v[24:25], v[56:57], v[24:25]
	v_mov_b32_e32 v54, v23
	v_mov_b32_e32 v55, v25
	v_mov_b32_e32 v50, v22
	v_mov_b32_e32 v51, v24
	v_pk_mul_f32 v[54:55], v[54:55], v[54:55]
	v_cvt_f32_f16_sdwa v59, v21 dst_sel:DWORD dst_unused:UNUSED_PAD src0_sel:WORD_1
	v_pk_fma_f32 v[50:51], v[50:51], v[50:51], v[54:55]
	v_cvt_f32_f16_e32 v58, v21
	v_pk_add_f32 v[54:55], v[50:51], v[50:51] op_sel:[0,1] op_sel_hi:[1,0]
	v_cvt_f32_f16_sdwa v51, v20 dst_sel:DWORD dst_unused:UNUSED_PAD src0_sel:WORD_1
	v_cvt_f32_f16_e32 v50, v20
	v_lshlrev_b32_e32 v56, 16, v18
	v_and_b32_e32 v57, 0xffff0000, v18
	v_lshlrev_b32_e32 v18, 16, v19
	v_pk_add_f32 v[20:21], v[50:51], v[56:57]
	v_and_b32_e32 v19, 0xffff0000, v19
	v_pk_add_f32 v[50:51], v[58:59], v[18:19]
	v_mul_f32_e32 v18, v21, v21
	v_pk_fma_f32 v[56:57], v[20:21], v[20:21], v[18:19] op_sel_hi:[1,1,0]
	v_mul_f32_e32 v18, v51, v51
	v_pk_fma_f32 v[58:59], v[50:51], v[50:51], v[18:19] op_sel_hi:[1,1,0]
	v_cvt_f32_f16_sdwa v19, v46 dst_sel:DWORD dst_unused:UNUSED_PAD src0_sel:WORD_1
; __device__ __forceinline__ float bf_lo(unsigned u) { return __uint_as_float(u << 16); }
; __device__ __forceinline__ float bf_hi(unsigned u) { return __uint_as_float(u & 0xffff0000u); }
; __device__ __forceinline__ void phase_final(const _Float16* xin_h, const bf16_t* dl, const float* g, float* out) {
;     ...
;         for (int q = 0; q < 2; ++q) { const int row = row0 + q * NW; float s = 0.f;
;             if (row >= MTOK) break;
; #pragma unroll
;             for (int j = 0; j < 8; ++j) { v[q][j].x += bf_lo(d[q][j].x); v[q][j].y += bf_hi(d[q][j].x); v[q][j].z += bf_lo(d[q][j].y); v[q][j].w += bf_hi(d[q][j].y);
;                 s += (v[q][j].x * v[q][j].x + v[q][j].y * v[q][j].y) + (v[q][j].z * v[q][j].z + v[q][j].w * v[q][j].w); }
;             const float rstd = 1.f / sqrtf(wave_sum(s) * (1.f / DM) + 1e-6f);
;             f32x4* o = (f32x4*)(out + (size_t)row * DM) + lane;
; #pragma unroll
;             for (int j = 0; j < 8; ++j) o[64 * j] = v[q][j] * rstd * *(const f32x4*)(g + 4 * lane + 256 * j); }
	v_cvt_f32_f16_e32 v18, v46
	v_cvt_f32_f16_sdwa v63, v47 dst_sel:DWORD dst_unused:UNUSED_PAD src0_sel:WORD_1
	v_cvt_f32_f16_e32 v62, v47
	v_lshlrev_b32_e32 v60, 16, v48
	v_and_b32_e32 v61, 0xffff0000, v48
	v_lshlrev_b32_e32 v46, 16, v49
	v_and_b32_e32 v47, 0xffff0000, v49
	v_pk_add_f32 v[18:19], v[18:19], v[60:61]
	v_pk_add_f32 v[46:47], v[62:63], v[46:47]
	v_pk_mul_f32 v[48:49], v[18:19], v[18:19]
	v_pk_mul_f32 v[60:61], v[46:47], v[46:47]
	v_mov_b32_e32 v53, v48
	v_mov_b32_e32 v55, v49
	v_mov_b32_e32 v57, v60
	v_mov_b32_e32 v59, v61
	v_pk_add_f32 v[48:49], v[52:53], v[54:55]
	v_pk_add_f32 v[52:53], v[56:57], v[58:59]
	v_cvt_f32_f16_sdwa v57, v43 dst_sel:DWORD dst_unused:UNUSED_PAD src0_sel:WORD_1
	v_pk_add_f32 v[48:49], v[48:49], v[52:53]
	v_cvt_f32_f16_sdwa v53, v42 dst_sel:DWORD dst_unused:UNUSED_PAD src0_sel:WORD_1
	v_cvt_f32_f16_e32 v52, v42
	v_cvt_f32_f16_e32 v56, v43
	v_lshlrev_b32_e32 v54, 16, v44
	v_and_b32_e32 v55, 0xffff0000, v44
	v_lshlrev_b32_e32 v44, 16, v45
	v_and_b32_e32 v45, 0xffff0000, v45
	v_pk_add_f32 v[42:43], v[52:53], v[54:55]
	v_pk_add_f32 v[44:45], v[56:57], v[44:45]
	v_cvt_f32_f16_sdwa v59, v39 dst_sel:DWORD dst_unused:UNUSED_PAD src0_sel:WORD_1
	v_cvt_f32_f16_e32 v58, v39
	v_mov_b32_e32 v54, v43
	v_mov_b32_e32 v55, v45
	v_mov_b32_e32 v52, v42
	v_mov_b32_e32 v53, v44
	v_pk_mul_f32 v[54:55], v[54:55], v[54:55]
	v_lshlrev_b32_e32 v56, 16, v40
	v_pk_fma_f32 v[52:53], v[52:53], v[52:53], v[54:55]
	v_cvt_f32_f16_sdwa v55, v38 dst_sel:DWORD dst_unused:UNUSED_PAD src0_sel:WORD_1
	v_cvt_f32_f16_e32 v54, v38
	v_and_b32_e32 v57, 0xffff0000, v40
	v_lshlrev_b32_e32 v40, 16, v41
	v_and_b32_e32 v41, 0xffff0000, v41
	v_pk_add_f32 v[40:41], v[58:59], v[40:41]
	v_cvt_f32_f16_sdwa v59, v34 dst_sel:DWORD dst_unused:UNUSED_PAD src0_sel:WORD_1
	v_cvt_f32_f16_e32 v58, v34
	v_cvt_f32_f16_sdwa v63, v35 dst_sel:DWORD dst_unused:UNUSED_PAD src0_sel:WORD_1
	v_cvt_f32_f16_e32 v62, v35
	v_pk_add_f32 v[38:39], v[54:55], v[56:57]
	v_lshlrev_b32_e32 v60, 16, v36
	v_and_b32_e32 v61, 0xffff0000, v36
	v_lshlrev_b32_e32 v34, 16, v37
	v_and_b32_e32 v35, 0xffff0000, v37
	v_mul_f32_e32 v54, v39, v39
	v_mul_f32_e32 v56, v41, v41
	v_pk_add_f32 v[58:59], v[58:59], v[60:61]
	v_pk_add_f32 v[60:61], v[62:63], v[34:35]
	v_pk_add_f32 v[48:49], v[48:49], v[48:49] op_sel:[0,1] op_sel_hi:[1,0]
	v_pk_add_f32 v[52:53], v[52:53], v[52:53] op_sel:[0,1] op_sel_hi:[1,0]
	v_pk_fma_f32 v[54:55], v[38:39], v[38:39], v[54:55] op_sel_hi:[1,1,0]
	v_pk_fma_f32 v[56:57], v[40:41], v[40:41], v[56:57] op_sel_hi:[1,1,0]
	v_pk_mul_f32 v[34:35], v[58:59], v[58:59]
	v_pk_mul_f32 v[36:37], v[60:61], v[60:61]
	v_mov_b32_e32 v49, v34
	v_mov_b32_e32 v53, v35
	v_mov_b32_e32 v55, v36
	v_mov_b32_e32 v57, v37
	v_pk_add_f32 v[34:35], v[48:49], v[52:53]
	v_pk_add_f32 v[36:37], v[54:55], v[56:57]
	s_ashr_i32 s13, s12, 31
	v_pk_add_f32 v[48:49], v[34:35], v[36:37]
	global_load_dwordx4 v[34:37], v[8:9], off
	v_add_f32_e32 v48, v48, v49
	ds_bpermute_b32 v0, v0, v48
	s_waitcnt lgkmcnt(0)
	v_add_f32_e32 v0, v48, v0
	ds_bpermute_b32 v48, v82, v0
	s_waitcnt lgkmcnt(0)
	v_add_f32_e32 v0, v0, v48
	ds_bpermute_b32 v48, v83, v0
	s_waitcnt lgkmcnt(0)
	v_add_f32_e32 v0, v0, v48
	ds_bpermute_b32 v48, v84, v0
	s_waitcnt lgkmcnt(0)
	v_add_f32_e32 v0, v0, v48
	ds_bpermute_b32 v48, v85, v0
	s_waitcnt lgkmcnt(0)
	v_add_f32_e32 v0, v0, v48
	ds_bpermute_b32 v48, v86, v0
	s_waitcnt lgkmcnt(0)
; __device__ __forceinline__ void phase_final(const _Float16* xin_h, const bf16_t* dl, const float* g, float* out) {
;     ...
;             const float rstd = 1.f / sqrtf(wave_sum(s) * (1.f / DM) + 1e-6f);
;             f32x4* o = (f32x4*)(out + (size_t)row * DM) + lane;
; #pragma unroll
;             for (int j = 0; j < 8; ++j) o[64 * j] = v[q][j] * rstd * *(const f32x4*)(g + 4 * lane + 256 * j); }
	v_add_f32_e32 v0, v0, v48
	v_fmamk_f32 v0, v0, 0x3a000000, v181
	v_mul_f32_e32 v48, 0x4f800000, v0
	v_cmp_gt_f32_e32 vcc, s7, v0
	s_nop 1
	v_cndmask_b32_e32 v0, v0, v48, vcc
	v_sqrt_f32_e32 v48, v0
	s_nop 0
	v_add_u32_e32 v49, -1, v48
	v_fma_f32 v52, -v49, v48, v0
	v_cmp_ge_f32_e64 s[40:41], 0, v52
	v_add_u32_e32 v52, 1, v48
	s_nop 0
	v_cndmask_b32_e64 v49, v48, v49, s[40:41]
	v_fma_f32 v48, -v52, v48, v0
	v_cmp_lt_f32_e64 s[40:41], 0, v48
	s_nop 1
	v_cndmask_b32_e64 v48, v49, v52, s[40:41]
	v_mul_f32_e32 v49, 0x37800000, v48
	v_cndmask_b32_e32 v48, v48, v49, vcc
	v_cmp_class_f32_e32 vcc, v0, v180
	s_nop 1
	v_cndmask_b32_e32 v0, v48, v0, vcc
	v_div_scale_f32 v48, s[2:3], v0, v0, 1.0
	v_rcp_f32_e32 v49, v48
	s_lshl_b64 s[2:3], s[12:13], 13
	v_fma_f32 v52, -v48, v49, 1.0
	v_fmac_f32_e32 v49, v52, v49
	v_div_scale_f32 v52, vcc, 1.0, v0, 1.0
	v_mul_f32_e32 v53, v52, v49
	v_fma_f32 v54, -v48, v53, v52
	v_fmac_f32_e32 v53, v54, v49
	v_fma_f32 v48, -v48, v53, v52
	v_div_fmas_f32 v48, v48, v49, v53
	v_div_fixup_f32 v0, v48, v0, 1.0
	v_pk_mul_f32 v[30:31], v[30:31], v[0:1] op_sel_hi:[1,0]
	v_pk_mul_f32 v[32:33], v[32:33], v[0:1] op_sel_hi:[1,0]
	v_lshl_add_u64 v[48:49], v[6:7], 0, s[2:3]
	s_waitcnt vmcnt(0)
	v_pk_mul_f32 v[32:33], v[36:37], v[32:33]
	v_pk_mul_f32 v[30:31], v[34:35], v[30:31]
	global_store_dwordx4 v[48:49], v[30:33], off
	s_nop 1
	v_mov_b32_e32 v30, v98
	v_mov_b32_e32 v31, v99
	v_mov_b32_e32 v32, v100
	v_mov_b32_e32 v33, v101
	v_pk_mul_f32 v[28:29], v[28:29], v[0:1] op_sel_hi:[1,0]
	v_pk_mul_f32 v[26:27], v[26:27], v[0:1] op_sel_hi:[1,0]
	v_pk_mul_f32 v[24:25], v[24:25], v[0:1] op_sel_hi:[1,0]
	v_pk_mul_f32 v[22:23], v[22:23], v[0:1] op_sel_hi:[1,0]
	v_pk_mul_f32 v[20:21], v[20:21], v[0:1] op_sel_hi:[1,0]
	v_pk_mul_f32 v[18:19], v[18:19], v[0:1] op_sel_hi:[1,0]
	v_pk_mul_f32 v[26:27], v[30:31], v[26:27]
	v_pk_mul_f32 v[28:29], v[32:33], v[28:29]
	global_store_dwordx4 v[48:49], v[26:29], off offset:1024
	s_nop 1
	v_mov_b32_e32 v26, v102
	v_mov_b32_e32 v27, v103
	v_mov_b32_e32 v28, v104
	v_mov_b32_e32 v29, v105
	v_pk_mul_f32 v[22:23], v[26:27], v[22:23]
	v_pk_mul_f32 v[24:25], v[28:29], v[24:25]
	global_store_dwordx4 v[48:49], v[22:25], off offset:2048
	s_nop 1
	v_mov_b32_e32 v22, v106
	v_mov_b32_e32 v23, v107
	v_mov_b32_e32 v24, v108
	v_mov_b32_e32 v25, v109
	v_pk_mul_f32 v[26:27], v[50:51], v[0:1] op_sel_hi:[1,0]
	v_pk_mul_f32 v[20:21], v[22:23], v[20:21]
	v_pk_mul_f32 v[22:23], v[24:25], v[26:27]
	global_store_dwordx4 v[48:49], v[20:23], off offset:3072
	s_nop 1
	v_mov_b32_e32 v20, v110
	v_mov_b32_e32 v21, v111
	v_mov_b32_e32 v22, v112
	v_mov_b32_e32 v23, v113
	v_add_co_u32_e32 v24, vcc, s6, v48
	v_pk_mul_f32 v[26:27], v[46:47], v[0:1] op_sel_hi:[1,0]
	s_nop 0
	v_addc_co_u32_e32 v25, vcc, 0, v49, vcc
	v_pk_mul_f32 v[18:19], v[18:19], v[20:21]
	v_pk_mul_f32 v[20:21], v[26:27], v[22:23]
	global_store_dwordx4 v[24:25], v[18:21], off
	s_nop 1
	v_mov_b32_e32 v18, v114
	v_mov_b32_e32 v19, v115
	v_mov_b32_e32 v20, v116
	v_mov_b32_e32 v21, v117
	v_pk_mul_f32 v[22:23], v[44:45], v[0:1] op_sel_hi:[1,0]
	v_pk_mul_f32 v[26:27], v[42:43], v[0:1] op_sel_hi:[1,0]
	v_pk_mul_f32 v[20:21], v[22:23], v[20:21]
	v_pk_mul_f32 v[18:19], v[26:27], v[18:19]
	global_store_dwordx4 v[24:25], v[18:21], off offset:1024
	s_nop 1
	v_mov_b32_e32 v18, v118
	v_mov_b32_e32 v19, v119
	v_mov_b32_e32 v20, v120
	v_mov_b32_e32 v21, v121
	v_pk_mul_f32 v[22:23], v[40:41], v[0:1] op_sel_hi:[1,0]
	v_pk_mul_f32 v[26:27], v[38:39], v[0:1] op_sel_hi:[1,0]
	v_pk_mul_f32 v[20:21], v[22:23], v[20:21]
	v_pk_mul_f32 v[18:19], v[26:27], v[18:19]
	global_store_dwordx4 v[24:25], v[18:21], off offset:2048
	s_nop 1
	v_mov_b32_e32 v18, v122
	v_mov_b32_e32 v19, v123
	v_mov_b32_e32 v20, v124
	v_mov_b32_e32 v21, v125
	v_pk_mul_f32 v[22:23], v[60:61], v[0:1] op_sel_hi:[1,0]
	v_pk_mul_f32 v[26:27], v[58:59], v[0:1] op_sel_hi:[1,0]
	v_pk_mul_f32 v[20:21], v[22:23], v[20:21]
	v_pk_mul_f32 v[18:19], v[26:27], v[18:19]
	global_store_dwordx4 v[24:25], v[18:21], off offset:3072
	s_branch .LBB0_754
